# prep phase rewritten (4 rows per pass, loads issued together, interleaved wave reductions) + sgu stats loads de-serialized; bit-exact
# speedup vs baseline: 1.0044x; 1.0044x over previous
; __device__ __forceinline__ float bf_lo(unsigned u) { return __uint_as_float(u << 16); }
; __device__ __forceinline__ float bf_hi(unsigned u) { return __uint_as_float(u & 0xffff0000u); }
; __device__ __forceinline__ void sgu_phase(LAS unsigned char* lds, const bf16_t* U, const bf16_t* VTg, const float* vg, const float* vb, const float* wsp, const float* bsp, bf16_t* Gout, int bid, int G, const int tid) {
;     ...
;             for (int pass = 0; pass < 64; ++pass) {
;                 const u32x4 t = *(const u32x4*)((const char*)(VTg + (size_t)(pass * 32) * M + r0) + (unsigned)((rg * M + tc * 8) * 2));
;                 const float v[8] = {bf_lo(t.x), bf_hi(t.x), bf_lo(t.y), bf_hi(t.y), bf_lo(t.z), bf_hi(t.z), bf_lo(t.w), bf_hi(t.w)};
; #pragma unroll
;                 for (int e = 0; e < 8; ++e) { s1[e] += v[e]; s2[e] += v[e] * v[e]; }
;             }
.LBB0_121:
	v_lshl_add_u64 v[16:17], v[122:123], 0, s[30:31]
	s_add_u32 s30, s30, 0x1000000
	s_addc_u32 s31, s31, 0
	s_mov_b32 s3, 0x2c200000
	v_add_co_u32_e32 v18, vcc, s3, v16
	s_nop 1
	v_addc_co_u32_e32 v19, vcc, 0, v17, vcc
	global_load_dwordx4 v[210:213], v[18:19], off
	s_mov_b32 s3, 0x2c400000
	v_add_co_u32_e32 v18, vcc, s3, v16
	s_nop 1
	v_addc_co_u32_e32 v19, vcc, 0, v17, vcc
	global_load_dwordx4 v[214:217], v[18:19], off
	s_mov_b32 s3, 0x2c600000
	v_add_co_u32_e32 v18, vcc, s3, v16
	s_nop 1
	v_addc_co_u32_e32 v19, vcc, 0, v17, vcc
	global_load_dwordx4 v[218:221], v[18:19], off
	s_mov_b32 s3, 0x2c800000
	v_add_co_u32_e32 v18, vcc, s3, v16
	s_nop 1
	v_addc_co_u32_e32 v19, vcc, 0, v17, vcc
	global_load_dwordx4 v[222:225], v[18:19], off
	s_mov_b32 s3, 0x2ca00000
	v_add_co_u32_e32 v18, vcc, s3, v16
	s_nop 1
	v_addc_co_u32_e32 v19, vcc, 0, v17, vcc
	global_load_dwordx4 v[226:229], v[18:19], off
	s_mov_b32 s3, 0x2cc00000
	v_add_co_u32_e32 v18, vcc, s3, v16
	s_nop 1
	v_addc_co_u32_e32 v19, vcc, 0, v17, vcc
	global_load_dwordx4 v[240:243], v[18:19], off
	s_mov_b32 s3, 0x2ce00000
	v_add_co_u32_e32 v18, vcc, s3, v16
	s_nop 1
	v_addc_co_u32_e32 v19, vcc, 0, v17, vcc
	global_load_dwordx4 v[244:247], v[18:19], off
	s_mov_b32 s3, 0x2d000000
	v_add_co_u32_e32 v18, vcc, s3, v16
	s_nop 1
	v_addc_co_u32_e32 v19, vcc, 0, v17, vcc
	global_load_dwordx4 v[28:31], v[18:19], off
	s_waitcnt vmcnt(7)
	v_lshlrev_b32_e32 v20, 16, v210
	v_and_b32_e32 v22, 0xffff0000, v210
	v_lshlrev_b32_e32 v24, 16, v211
	v_and_b32_e32 v26, 0xffff0000, v211
	v_mul_f32_e32 v21, v20, v20
	v_mul_f32_e32 v23, v22, v22
	v_mul_f32_e32 v25, v24, v24
	v_mul_f32_e32 v27, v26, v26
	v_pk_add_f32 v[4:5], v[4:5], v[20:21]
	v_pk_add_f32 v[6:7], v[6:7], v[22:23]
	v_pk_add_f32 v[12:13], v[12:13], v[24:25]
	v_pk_add_f32 v[14:15], v[14:15], v[26:27]
	v_lshlrev_b32_e32 v20, 16, v212
	v_and_b32_e32 v22, 0xffff0000, v212
	v_lshlrev_b32_e32 v24, 16, v213
	v_and_b32_e32 v26, 0xffff0000, v213
	v_mul_f32_e32 v21, v20, v20
	v_mul_f32_e32 v23, v22, v22
	v_mul_f32_e32 v25, v24, v24
	v_mul_f32_e32 v27, v26, v26
	v_pk_add_f32 v[8:9], v[8:9], v[20:21]
	v_pk_add_f32 v[10:11], v[10:11], v[22:23]
	v_pk_add_f32 v[0:1], v[0:1], v[24:25]
	v_pk_add_f32 v[2:3], v[2:3], v[26:27]
	s_waitcnt vmcnt(6)
	v_lshlrev_b32_e32 v20, 16, v214
	v_and_b32_e32 v22, 0xffff0000, v214
	v_lshlrev_b32_e32 v24, 16, v215
	v_and_b32_e32 v26, 0xffff0000, v215
	v_mul_f32_e32 v21, v20, v20
	v_mul_f32_e32 v23, v22, v22
	v_mul_f32_e32 v25, v24, v24
	v_mul_f32_e32 v27, v26, v26
	v_pk_add_f32 v[4:5], v[4:5], v[20:21]
	v_pk_add_f32 v[6:7], v[6:7], v[22:23]
	v_pk_add_f32 v[12:13], v[12:13], v[24:25]
	v_pk_add_f32 v[14:15], v[14:15], v[26:27]
	v_lshlrev_b32_e32 v20, 16, v216
	v_and_b32_e32 v22, 0xffff0000, v216
	v_lshlrev_b32_e32 v24, 16, v217
	v_and_b32_e32 v26, 0xffff0000, v217
	v_mul_f32_e32 v21, v20, v20
	v_mul_f32_e32 v23, v22, v22
	v_mul_f32_e32 v25, v24, v24
	v_mul_f32_e32 v27, v26, v26
	v_pk_add_f32 v[8:9], v[8:9], v[20:21]
	v_pk_add_f32 v[10:11], v[10:11], v[22:23]
	v_pk_add_f32 v[0:1], v[0:1], v[24:25]
	v_pk_add_f32 v[2:3], v[2:3], v[26:27]
	s_waitcnt vmcnt(5)
	v_lshlrev_b32_e32 v20, 16, v218
	v_and_b32_e32 v22, 0xffff0000, v218
	v_lshlrev_b32_e32 v24, 16, v219
	v_and_b32_e32 v26, 0xffff0000, v219
	v_mul_f32_e32 v21, v20, v20
	v_mul_f32_e32 v23, v22, v22
	v_mul_f32_e32 v25, v24, v24
	v_mul_f32_e32 v27, v26, v26
	v_pk_add_f32 v[4:5], v[4:5], v[20:21]
	v_pk_add_f32 v[6:7], v[6:7], v[22:23]
	v_pk_add_f32 v[12:13], v[12:13], v[24:25]
	v_pk_add_f32 v[14:15], v[14:15], v[26:27]
	v_lshlrev_b32_e32 v20, 16, v220
	v_and_b32_e32 v22, 0xffff0000, v220
	v_lshlrev_b32_e32 v24, 16, v221
	v_and_b32_e32 v26, 0xffff0000, v221
	v_mul_f32_e32 v21, v20, v20
	v_mul_f32_e32 v23, v22, v22
	v_mul_f32_e32 v25, v24, v24
	v_mul_f32_e32 v27, v26, v26
	v_pk_add_f32 v[8:9], v[8:9], v[20:21]
	v_pk_add_f32 v[10:11], v[10:11], v[22:23]
	v_pk_add_f32 v[0:1], v[0:1], v[24:25]
	v_pk_add_f32 v[2:3], v[2:3], v[26:27]
	s_waitcnt vmcnt(4)
; #define LAS __attribute__((address_space(3)))
; __device__ __forceinline__ float bf_lo(unsigned u) { return __uint_as_float(u << 16); }
; __device__ __forceinline__ float bf_hi(unsigned u) { return __uint_as_float(u & 0xffff0000u); }
; __device__ __forceinline__ void sgu_phase(LAS unsigned char* lds, const bf16_t* U, const bf16_t* VTg, const float* vg, const float* vb, const float* wsp, const float* bsp, bf16_t* Gout, int bid, int G, const int tid) {
;     ...
;             for (int pass = 0; pass < 64; ++pass) {
;                 const u32x4 t = *(const u32x4*)((const char*)(VTg + (size_t)(pass * 32) * M + r0) + (unsigned)((rg * M + tc * 8) * 2));
;                 const float v[8] = {bf_lo(t.x), bf_hi(t.x), bf_lo(t.y), bf_hi(t.y), bf_lo(t.z), bf_hi(t.z), bf_lo(t.w), bf_hi(t.w)};
; #pragma unroll
;                 for (int e = 0; e < 8; ++e) { s1[e] += v[e]; s2[e] += v[e] * v[e]; }
;             }
; #pragma unroll
;             for (int e = 0; e < 8; ++e) *(LAS f32x2*)(red + (rg * 128 + tc * 8 + e) * 2) = (f32x2){s1[e], s2[e]};
;         }
;         __syncthreads();
;         if (tid < 128) {
	v_lshlrev_b32_e32 v20, 16, v222
	v_and_b32_e32 v22, 0xffff0000, v222
	v_lshlrev_b32_e32 v24, 16, v223
	v_and_b32_e32 v26, 0xffff0000, v223
	v_mul_f32_e32 v21, v20, v20
	v_mul_f32_e32 v23, v22, v22
	v_mul_f32_e32 v25, v24, v24
	v_mul_f32_e32 v27, v26, v26
	v_pk_add_f32 v[4:5], v[4:5], v[20:21]
	v_pk_add_f32 v[6:7], v[6:7], v[22:23]
	v_pk_add_f32 v[12:13], v[12:13], v[24:25]
	v_pk_add_f32 v[14:15], v[14:15], v[26:27]
	v_lshlrev_b32_e32 v20, 16, v224
	v_and_b32_e32 v22, 0xffff0000, v224
	v_lshlrev_b32_e32 v24, 16, v225
	v_and_b32_e32 v26, 0xffff0000, v225
	v_mul_f32_e32 v21, v20, v20
	v_mul_f32_e32 v23, v22, v22
	v_mul_f32_e32 v25, v24, v24
	v_mul_f32_e32 v27, v26, v26
	v_pk_add_f32 v[8:9], v[8:9], v[20:21]
	v_pk_add_f32 v[10:11], v[10:11], v[22:23]
	v_pk_add_f32 v[0:1], v[0:1], v[24:25]
	v_pk_add_f32 v[2:3], v[2:3], v[26:27]
	s_waitcnt vmcnt(3)
	v_lshlrev_b32_e32 v20, 16, v226
	v_and_b32_e32 v22, 0xffff0000, v226
	v_lshlrev_b32_e32 v24, 16, v227
	v_and_b32_e32 v26, 0xffff0000, v227
	v_mul_f32_e32 v21, v20, v20
	v_mul_f32_e32 v23, v22, v22
	v_mul_f32_e32 v25, v24, v24
	v_mul_f32_e32 v27, v26, v26
	v_pk_add_f32 v[4:5], v[4:5], v[20:21]
	v_pk_add_f32 v[6:7], v[6:7], v[22:23]
	v_pk_add_f32 v[12:13], v[12:13], v[24:25]
	v_pk_add_f32 v[14:15], v[14:15], v[26:27]
	v_lshlrev_b32_e32 v20, 16, v228
	v_and_b32_e32 v22, 0xffff0000, v228
	v_lshlrev_b32_e32 v24, 16, v229
	v_and_b32_e32 v26, 0xffff0000, v229
	v_mul_f32_e32 v21, v20, v20
	v_mul_f32_e32 v23, v22, v22
	v_mul_f32_e32 v25, v24, v24
	v_mul_f32_e32 v27, v26, v26
	v_pk_add_f32 v[8:9], v[8:9], v[20:21]
	v_pk_add_f32 v[10:11], v[10:11], v[22:23]
	v_pk_add_f32 v[0:1], v[0:1], v[24:25]
	v_pk_add_f32 v[2:3], v[2:3], v[26:27]
	s_waitcnt vmcnt(2)
	v_lshlrev_b32_e32 v20, 16, v240
	v_and_b32_e32 v22, 0xffff0000, v240
	v_lshlrev_b32_e32 v24, 16, v241
	v_and_b32_e32 v26, 0xffff0000, v241
	v_mul_f32_e32 v21, v20, v20
	v_mul_f32_e32 v23, v22, v22
	v_mul_f32_e32 v25, v24, v24
	v_mul_f32_e32 v27, v26, v26
	v_pk_add_f32 v[4:5], v[4:5], v[20:21]
	v_pk_add_f32 v[6:7], v[6:7], v[22:23]
	v_pk_add_f32 v[12:13], v[12:13], v[24:25]
	v_pk_add_f32 v[14:15], v[14:15], v[26:27]
	v_lshlrev_b32_e32 v20, 16, v242
	v_and_b32_e32 v22, 0xffff0000, v242
	v_lshlrev_b32_e32 v24, 16, v243
	v_and_b32_e32 v26, 0xffff0000, v243
	v_mul_f32_e32 v21, v20, v20
	v_mul_f32_e32 v23, v22, v22
	v_mul_f32_e32 v25, v24, v24
	v_mul_f32_e32 v27, v26, v26
	v_pk_add_f32 v[8:9], v[8:9], v[20:21]
	v_pk_add_f32 v[10:11], v[10:11], v[22:23]
	v_pk_add_f32 v[0:1], v[0:1], v[24:25]
	v_pk_add_f32 v[2:3], v[2:3], v[26:27]
	s_waitcnt vmcnt(1)
	v_lshlrev_b32_e32 v20, 16, v244
	v_and_b32_e32 v22, 0xffff0000, v244
	v_lshlrev_b32_e32 v24, 16, v245
	v_and_b32_e32 v26, 0xffff0000, v245
	v_mul_f32_e32 v21, v20, v20
	v_mul_f32_e32 v23, v22, v22
	v_mul_f32_e32 v25, v24, v24
	v_mul_f32_e32 v27, v26, v26
	v_pk_add_f32 v[4:5], v[4:5], v[20:21]
	v_pk_add_f32 v[6:7], v[6:7], v[22:23]
	v_pk_add_f32 v[12:13], v[12:13], v[24:25]
	v_pk_add_f32 v[14:15], v[14:15], v[26:27]
	v_lshlrev_b32_e32 v20, 16, v246
	v_and_b32_e32 v22, 0xffff0000, v246
	v_lshlrev_b32_e32 v24, 16, v247
	v_and_b32_e32 v26, 0xffff0000, v247
	v_mul_f32_e32 v21, v20, v20
	v_mul_f32_e32 v23, v22, v22
	v_mul_f32_e32 v25, v24, v24
	v_mul_f32_e32 v27, v26, v26
	v_pk_add_f32 v[8:9], v[8:9], v[20:21]
	v_pk_add_f32 v[10:11], v[10:11], v[22:23]
	v_pk_add_f32 v[0:1], v[0:1], v[24:25]
	v_pk_add_f32 v[2:3], v[2:3], v[26:27]
	s_waitcnt vmcnt(0)
	v_lshlrev_b32_e32 v20, 16, v28
	v_and_b32_e32 v22, 0xffff0000, v28
	v_lshlrev_b32_e32 v24, 16, v29
	v_and_b32_e32 v26, 0xffff0000, v29
	v_mul_f32_e32 v21, v20, v20
	v_mul_f32_e32 v23, v22, v22
	v_mul_f32_e32 v25, v24, v24
	v_mul_f32_e32 v27, v26, v26
	v_pk_add_f32 v[4:5], v[4:5], v[20:21]
	v_pk_add_f32 v[6:7], v[6:7], v[22:23]
	v_pk_add_f32 v[12:13], v[12:13], v[24:25]
	v_pk_add_f32 v[14:15], v[14:15], v[26:27]
	v_lshlrev_b32_e32 v20, 16, v30
	v_and_b32_e32 v22, 0xffff0000, v30
	v_lshlrev_b32_e32 v24, 16, v31
	v_and_b32_e32 v26, 0xffff0000, v31
	v_mul_f32_e32 v21, v20, v20
	v_mul_f32_e32 v23, v22, v22
	v_mul_f32_e32 v25, v24, v24
	v_mul_f32_e32 v27, v26, v26
	v_pk_add_f32 v[8:9], v[8:9], v[20:21]
	v_pk_add_f32 v[10:11], v[10:11], v[22:23]
	v_pk_add_f32 v[0:1], v[0:1], v[24:25]
	v_pk_add_f32 v[2:3], v[2:3], v[26:27]
	s_cmp_lg_u32 s30, 0x8000000
	s_cbranch_scc1 .LBB0_121
	ds_write_b128 v159, v[4:7] offset:34816
	ds_write_b128 v159, v[12:15] offset:34832
	ds_write_b128 v159, v[8:11] offset:34848
	ds_write_b128 v159, v[0:3] offset:34864
	s_waitcnt lgkmcnt(0)
	s_barrier
	s_mov_b64 s[30:31], exec
	v_readlane_b32 vcc_lo, v255, 16
	v_readlane_b32 vcc_hi, v255, 17
	s_and_b64 vcc, s[30:31], vcc
	s_mov_b64 exec, vcc
	s_cbranch_execz .LBB0_126
	v_mov_b32_e32 v0, 0
	s_mov_b32 s3, 0
	v_mov_b32_e32 v1, v0

; __device__ __forceinline__ float bf_lo(unsigned u) { return __uint_as_float(u << 16); }
; __device__ __forceinline__ float bf_hi(unsigned u) { return __uint_as_float(u & 0xffff0000u); }
; __device__ __forceinline__ void prep_phase(bf16_t* P, const float* qg, const float* kvg, const float* cs, int gw, int NGW, int lane) {
;     for (int m = gw; m < M; m += NGW) {
;         bf16_t* pr = P + (size_t)m * P_LD;
; #pragma unroll
;         for (int part = 0; part < 2; ++part) {
;             bf16_t* q = pr + part * 512 + lane * 8;
;             const float* g = (part ? kvg : qg) + lane * 8;
;             const u32x4 t = *(const u32x4*)q;
;             float v[8] = {bf_lo(t.x), bf_hi(t.x), bf_lo(t.y), bf_hi(t.y), bf_lo(t.z), bf_hi(t.z), bf_lo(t.w), bf_hi(t.w)};
;             float ss = 0.f;
; #pragma unroll
;             for (int e = 0; e < 8; ++e) ss += v[e] * v[e];
;             const float rs = __builtin_amdgcn_rsqf(wave_sum(ss) * (1.0f / 512.0f) + EPS);
;             const f32x4 g0 = *(const f32x4*)g, g1 = *(const f32x4*)(g + 4);
.LBB0_156:
	s_load_dwordx2 s[6:7], s[0:1], 0x78
	s_waitcnt lgkmcnt(0)
	s_load_dwordx2 s[20:21], s[0:1], 0x80
	s_waitcnt lgkmcnt(0)
	s_cmpk_gt_i32 s14, 0x7fff
	s_cbranch_scc1 .LBB0_161
	v_lshlrev_b32_e32 v0, 5, v239
	global_load_dwordx4 v[86:89], v0, s[6:7]
	global_load_dwordx4 v[90:93], v0, s[6:7] offset:16
	global_load_dwordx4 v[94:97], v0, s[20:21]
	global_load_dwordx4 v[98:101], v0, s[20:21] offset:16
	v_xor_b32_e32 v64, 1, v236
	v_xor_b32_e32 v65, 2, v236
	v_xor_b32_e32 v66, 4, v236
	v_xor_b32_e32 v67, 8, v236
	v_xor_b32_e32 v68, 16, v236
	v_xor_b32_e32 v69, 32, v236
	v_lshlrev_b32_e32 v64, 2, v64
	v_lshlrev_b32_e32 v65, 2, v65
	v_lshlrev_b32_e32 v66, 2, v66
	v_lshlrev_b32_e32 v67, 2, v67
	v_lshlrev_b32_e32 v68, 2, v68
	v_lshlrev_b32_e32 v69, 2, v69
	v_lshlrev_b32_e32 v13, 4, v239
	v_lshlrev_b32_e32 v14, 1, v239
	v_lshlrev_b32_e32 v15, 3, v239
	v_add_u32_e32 v0, 0x1880, v14
	s_add_u32 s30, s24, 0x24200000
	s_addc_u32 s31, s25, 0
	s_add_u32 s4, s24, 0x13a00000
	s_addc_u32 s5, s25, 0
	s_mov_b32 s3, s14
.Lprep_rows:
	s_add_i32 s17, s3, s16
	s_cmp_lt_i32 s17, 0x8000
	s_cselect_b32 vcc_lo, s17, s3
	s_add_i32 s17, s17, s16
	s_cmp_lt_i32 s17, 0x8000
	s_cselect_b32 s13, s17, s3
	s_add_i32 s17, s17, s16
	s_cmp_lt_i32 s17, 0x8000
	s_cselect_b32 s15, s17, s3
	s_mul_i32 s17, s3, 0x1a00
	v_add_u32_e32 v1, s17, v13
	v_add_u32_e32 v5, s17, v14
	s_lshl_b32 s17, s3, 8
	v_add_u32_e32 v9, s17, v15
	s_mul_i32 s17, vcc_lo, 0x1a00
	v_add_u32_e32 v2, s17, v13
	v_add_u32_e32 v6, s17, v14
	s_lshl_b32 s17, vcc_lo, 8
	v_add_u32_e32 v10, s17, v15
	s_mul_i32 s17, s13, 0x1a00
	v_add_u32_e32 v3, s17, v13
	v_add_u32_e32 v7, s17, v14
	s_lshl_b32 s17, s13, 8
	v_add_u32_e32 v11, s17, v15
	s_mul_i32 s17, s15, 0x1a00
	v_add_u32_e32 v4, s17, v13
	v_add_u32_e32 v8, s17, v14
	s_lshl_b32 s17, s15, 8
	v_add_u32_e32 v12, s17, v15
	global_load_dwordx4 v[16:19], v1, s[30:31]
	global_load_dwordx4 v[20:23], v1, s[30:31] offset:1024
	global_load_dwordx4 v[24:27], v2, s[30:31]
	global_load_dwordx4 v[28:31], v2, s[30:31] offset:1024
	global_load_dwordx4 v[32:35], v3, s[30:31]
	global_load_dwordx4 v[36:39], v3, s[30:31] offset:1024
	global_load_dwordx4 v[40:43], v4, s[30:31]
	global_load_dwordx4 v[44:47], v4, s[30:31] offset:1024
	global_load_ushort v48, v5, s[30:31] offset:2048
	global_load_ushort v52, v5, s[30:31] offset:2112
	global_load_dwordx2 v[56:57], v9, s[4:5]
	global_load_ushort v49, v6, s[30:31] offset:2048
	global_load_ushort v53, v6, s[30:31] offset:2112
	global_load_dwordx2 v[58:59], v10, s[4:5]
	global_load_ushort v50, v7, s[30:31] offset:2048
	global_load_ushort v54, v7, s[30:31] offset:2112
	global_load_dwordx2 v[60:61], v11, s[4:5]
	global_load_ushort v51, v8, s[30:31] offset:2048
	global_load_ushort v55, v8, s[30:31] offset:2112
	global_load_dwordx2 v[62:63], v12, s[4:5]
	s_waitcnt vmcnt(0)
	v_lshlrev_b32_e32 v102, 16, v16
	v_and_b32_e32 v103, 0xffff0000, v16
	v_lshlrev_b32_e32 v104, 16, v17
	v_and_b32_e32 v105, 0xffff0000, v17
	v_lshlrev_b32_e32 v106, 16, v18
	v_and_b32_e32 v107, 0xffff0000, v18
	v_lshlrev_b32_e32 v108, 16, v19
	v_and_b32_e32 v109, 0xffff0000, v19
	v_mul_f32_e32 v70, v103, v103
	v_fmac_f32_e32 v70, v102, v102
	v_fmac_f32_e32 v70, v104, v104
	v_fmac_f32_e32 v70, v105, v105
	v_fmac_f32_e32 v70, v106, v106
	v_fmac_f32_e32 v70, v107, v107
	v_fmac_f32_e32 v70, v108, v108
	v_fmac_f32_e32 v70, v109, v109
	v_lshlrev_b32_e32 v110, 16, v20
	v_and_b32_e32 v111, 0xffff0000, v20
	v_lshlrev_b32_e32 v112, 16, v21
	v_and_b32_e32 v113, 0xffff0000, v21
	v_lshlrev_b32_e32 v114, 16, v22
	v_and_b32_e32 v115, 0xffff0000, v22
	v_lshlrev_b32_e32 v116, 16, v23
	v_and_b32_e32 v117, 0xffff0000, v23
	v_mul_f32_e32 v71, v111, v111
	v_fmac_f32_e32 v71, v110, v110
	v_fmac_f32_e32 v71, v112, v112
	v_fmac_f32_e32 v71, v113, v113
	v_fmac_f32_e32 v71, v114, v114
	v_fmac_f32_e32 v71, v115, v115
	v_fmac_f32_e32 v71, v116, v116
	v_fmac_f32_e32 v71, v117, v117
	v_lshlrev_b32_e32 v118, 16, v24
	v_and_b32_e32 v119, 0xffff0000, v24
	v_lshlrev_b32_e32 v120, 16, v25
	v_and_b32_e32 v121, 0xffff0000, v25
	v_lshlrev_b32_e32 v122, 16, v26
	v_and_b32_e32 v123, 0xffff0000, v26
	v_lshlrev_b32_e32 v124, 16, v27
	v_and_b32_e32 v125, 0xffff0000, v27
	v_mul_f32_e32 v72, v119, v119
	v_fmac_f32_e32 v72, v118, v118
	v_fmac_f32_e32 v72, v120, v120
	v_fmac_f32_e32 v72, v121, v121
	v_fmac_f32_e32 v72, v122, v122
	v_fmac_f32_e32 v72, v123, v123
	v_fmac_f32_e32 v72, v124, v124
	v_fmac_f32_e32 v72, v125, v125
	v_lshlrev_b32_e32 v126, 16, v28
	v_and_b32_e32 v127, 0xffff0000, v28
	v_lshlrev_b32_e32 v128, 16, v29
	v_and_b32_e32 v129, 0xffff0000, v29
	v_lshlrev_b32_e32 v130, 16, v30
	v_and_b32_e32 v131, 0xffff0000, v30
	v_lshlrev_b32_e32 v132, 16, v31
	v_and_b32_e32 v133, 0xffff0000, v31
	v_mul_f32_e32 v73, v127, v127
	v_fmac_f32_e32 v73, v126, v126
	v_fmac_f32_e32 v73, v128, v128
	v_fmac_f32_e32 v73, v129, v129
	v_fmac_f32_e32 v73, v130, v130
	v_fmac_f32_e32 v73, v131, v131
	v_fmac_f32_e32 v73, v132, v132
	v_fmac_f32_e32 v73, v133, v133
	v_lshlrev_b32_e32 v134, 16, v32
	v_and_b32_e32 v135, 0xffff0000, v32
	v_lshlrev_b32_e32 v136, 16, v33
	v_and_b32_e32 v137, 0xffff0000, v33
	v_lshlrev_b32_e32 v138, 16, v34
	v_and_b32_e32 v139, 0xffff0000, v34
	v_lshlrev_b32_e32 v140, 16, v35
	v_and_b32_e32 v141, 0xffff0000, v35
	v_mul_f32_e32 v74, v135, v135
	v_fmac_f32_e32 v74, v134, v134
	v_fmac_f32_e32 v74, v136, v136
	v_fmac_f32_e32 v74, v137, v137
	v_fmac_f32_e32 v74, v138, v138
	v_fmac_f32_e32 v74, v139, v139
	v_fmac_f32_e32 v74, v140, v140
	v_fmac_f32_e32 v74, v141, v141
	v_lshlrev_b32_e32 v142, 16, v36
	v_and_b32_e32 v143, 0xffff0000, v36
	v_lshlrev_b32_e32 v144, 16, v37
	v_and_b32_e32 v145, 0xffff0000, v37
; __device__ __forceinline__ float bf_lo(unsigned u) { return __uint_as_float(u << 16); }
; __device__ __forceinline__ float bf_hi(unsigned u) { return __uint_as_float(u & 0xffff0000u); }
; __device__ __forceinline__ float wave_sum(float v) {
; #pragma unroll
;     for (int o = 1; o < 64; o <<= 1) v += __shfl_xor(v, o);
;     return v;
; }
; __device__ __forceinline__ void prep_phase(bf16_t* P, const float* qg, const float* kvg, const float* cs, int gw, int NGW, int lane) {
;     ...
;         for (int part = 0; part < 2; ++part) {
;             bf16_t* q = pr + part * 512 + lane * 8;
;             const float* g = (part ? kvg : qg) + lane * 8;
;             const u32x4 t = *(const u32x4*)q;
;             float v[8] = {bf_lo(t.x), bf_hi(t.x), bf_lo(t.y), bf_hi(t.y), bf_lo(t.z), bf_hi(t.z), bf_lo(t.w), bf_hi(t.w)};
;             float ss = 0.f;
; #pragma unroll
;             for (int e = 0; e < 8; ++e) ss += v[e] * v[e];
;             const float rs = __builtin_amdgcn_rsqf(wave_sum(ss) * (1.0f / 512.0f) + EPS);
	v_lshlrev_b32_e32 v146, 16, v38
	v_and_b32_e32 v147, 0xffff0000, v38
	v_lshlrev_b32_e32 v148, 16, v39
	v_and_b32_e32 v149, 0xffff0000, v39
	v_mul_f32_e32 v75, v143, v143
	v_fmac_f32_e32 v75, v142, v142
	v_fmac_f32_e32 v75, v144, v144
	v_fmac_f32_e32 v75, v145, v145
	v_fmac_f32_e32 v75, v146, v146
	v_fmac_f32_e32 v75, v147, v147
	v_fmac_f32_e32 v75, v148, v148
	v_fmac_f32_e32 v75, v149, v149
	v_lshlrev_b32_e32 v150, 16, v40
	v_and_b32_e32 v151, 0xffff0000, v40
	v_lshlrev_b32_e32 v152, 16, v41
	v_and_b32_e32 v153, 0xffff0000, v41
	v_lshlrev_b32_e32 v154, 16, v42
	v_and_b32_e32 v155, 0xffff0000, v42
	v_lshlrev_b32_e32 v156, 16, v43
	v_and_b32_e32 v157, 0xffff0000, v43
	v_mul_f32_e32 v76, v151, v151
	v_fmac_f32_e32 v76, v150, v150
	v_fmac_f32_e32 v76, v152, v152
	v_fmac_f32_e32 v76, v153, v153
	v_fmac_f32_e32 v76, v154, v154
	v_fmac_f32_e32 v76, v155, v155
	v_fmac_f32_e32 v76, v156, v156
	v_fmac_f32_e32 v76, v157, v157
	v_lshlrev_b32_e32 v158, 16, v44
	v_and_b32_e32 v159, 0xffff0000, v44
	v_lshlrev_b32_e32 v160, 16, v45
	v_and_b32_e32 v161, 0xffff0000, v45
	v_lshlrev_b32_e32 v162, 16, v46
	v_and_b32_e32 v163, 0xffff0000, v46
	v_lshlrev_b32_e32 v164, 16, v47
	v_and_b32_e32 v165, 0xffff0000, v47
	v_mul_f32_e32 v77, v159, v159
	v_fmac_f32_e32 v77, v158, v158
	v_fmac_f32_e32 v77, v160, v160
	v_fmac_f32_e32 v77, v161, v161
	v_fmac_f32_e32 v77, v162, v162
	v_fmac_f32_e32 v77, v163, v163
	v_fmac_f32_e32 v77, v164, v164
	v_fmac_f32_e32 v77, v165, v165
	ds_bpermute_b32 v78, v64, v70
	ds_bpermute_b32 v79, v64, v71
	ds_bpermute_b32 v80, v64, v72
	ds_bpermute_b32 v81, v64, v73
	ds_bpermute_b32 v82, v64, v74
	ds_bpermute_b32 v83, v64, v75
	ds_bpermute_b32 v84, v64, v76
	ds_bpermute_b32 v85, v64, v77
	s_waitcnt lgkmcnt(7)
	v_add_f32_e32 v70, v70, v78
	s_waitcnt lgkmcnt(6)
	v_add_f32_e32 v71, v71, v79
	s_waitcnt lgkmcnt(5)
	v_add_f32_e32 v72, v72, v80
	s_waitcnt lgkmcnt(4)
	v_add_f32_e32 v73, v73, v81
	s_waitcnt lgkmcnt(3)
	v_add_f32_e32 v74, v74, v82
	s_waitcnt lgkmcnt(2)
	v_add_f32_e32 v75, v75, v83
	s_waitcnt lgkmcnt(1)
	v_add_f32_e32 v76, v76, v84
	s_waitcnt lgkmcnt(0)
	v_add_f32_e32 v77, v77, v85
	ds_bpermute_b32 v78, v65, v70
	ds_bpermute_b32 v79, v65, v71
	ds_bpermute_b32 v80, v65, v72
	ds_bpermute_b32 v81, v65, v73
	ds_bpermute_b32 v82, v65, v74
	ds_bpermute_b32 v83, v65, v75
	ds_bpermute_b32 v84, v65, v76
	ds_bpermute_b32 v85, v65, v77
	s_waitcnt lgkmcnt(7)
	v_add_f32_e32 v70, v70, v78
	s_waitcnt lgkmcnt(6)
	v_add_f32_e32 v71, v71, v79
	s_waitcnt lgkmcnt(5)
	v_add_f32_e32 v72, v72, v80
	s_waitcnt lgkmcnt(4)
	v_add_f32_e32 v73, v73, v81
	s_waitcnt lgkmcnt(3)
	v_add_f32_e32 v74, v74, v82
	s_waitcnt lgkmcnt(2)
	v_add_f32_e32 v75, v75, v83
	s_waitcnt lgkmcnt(1)
	v_add_f32_e32 v76, v76, v84
	s_waitcnt lgkmcnt(0)
	v_add_f32_e32 v77, v77, v85
	ds_bpermute_b32 v78, v66, v70
	ds_bpermute_b32 v79, v66, v71
	ds_bpermute_b32 v80, v66, v72
	ds_bpermute_b32 v81, v66, v73
	ds_bpermute_b32 v82, v66, v74
	ds_bpermute_b32 v83, v66, v75
	ds_bpermute_b32 v84, v66, v76
	ds_bpermute_b32 v85, v66, v77
	s_waitcnt lgkmcnt(7)
	v_add_f32_e32 v70, v70, v78
	s_waitcnt lgkmcnt(6)
	v_add_f32_e32 v71, v71, v79
	s_waitcnt lgkmcnt(5)
	v_add_f32_e32 v72, v72, v80
	s_waitcnt lgkmcnt(4)
	v_add_f32_e32 v73, v73, v81
	s_waitcnt lgkmcnt(3)
	v_add_f32_e32 v74, v74, v82
	s_waitcnt lgkmcnt(2)
	v_add_f32_e32 v75, v75, v83
	s_waitcnt lgkmcnt(1)
	v_add_f32_e32 v76, v76, v84
	s_waitcnt lgkmcnt(0)
	v_add_f32_e32 v77, v77, v85
	ds_bpermute_b32 v78, v67, v70
	ds_bpermute_b32 v79, v67, v71
	ds_bpermute_b32 v80, v67, v72
	ds_bpermute_b32 v81, v67, v73
	ds_bpermute_b32 v82, v67, v74
	ds_bpermute_b32 v83, v67, v75
	ds_bpermute_b32 v84, v67, v76
	ds_bpermute_b32 v85, v67, v77
	s_waitcnt lgkmcnt(7)
	v_add_f32_e32 v70, v70, v78
	s_waitcnt lgkmcnt(6)
	v_add_f32_e32 v71, v71, v79
	s_waitcnt lgkmcnt(5)
	v_add_f32_e32 v72, v72, v80
	s_waitcnt lgkmcnt(4)
	v_add_f32_e32 v73, v73, v81
	s_waitcnt lgkmcnt(3)
	v_add_f32_e32 v74, v74, v82
	s_waitcnt lgkmcnt(2)
	v_add_f32_e32 v75, v75, v83
	s_waitcnt lgkmcnt(1)
	v_add_f32_e32 v76, v76, v84
	s_waitcnt lgkmcnt(0)
	v_add_f32_e32 v77, v77, v85
	ds_bpermute_b32 v78, v68, v70
	ds_bpermute_b32 v79, v68, v71
	ds_bpermute_b32 v80, v68, v72
	ds_bpermute_b32 v81, v68, v73
	ds_bpermute_b32 v82, v68, v74
	ds_bpermute_b32 v83, v68, v75
	ds_bpermute_b32 v84, v68, v76
	ds_bpermute_b32 v85, v68, v77
	s_waitcnt lgkmcnt(7)
	v_add_f32_e32 v70, v70, v78
	s_waitcnt lgkmcnt(6)
	v_add_f32_e32 v71, v71, v79
	s_waitcnt lgkmcnt(5)
	v_add_f32_e32 v72, v72, v80
	s_waitcnt lgkmcnt(4)
	v_add_f32_e32 v73, v73, v81
	s_waitcnt lgkmcnt(3)
	v_add_f32_e32 v74, v74, v82
	s_waitcnt lgkmcnt(2)
	v_add_f32_e32 v75, v75, v83
	s_waitcnt lgkmcnt(1)
	v_add_f32_e32 v76, v76, v84
	s_waitcnt lgkmcnt(0)
	v_add_f32_e32 v77, v77, v85
	ds_bpermute_b32 v78, v69, v70
	ds_bpermute_b32 v79, v69, v71
	ds_bpermute_b32 v80, v69, v72
	ds_bpermute_b32 v81, v69, v73
	ds_bpermute_b32 v82, v69, v74
	ds_bpermute_b32 v83, v69, v75
	ds_bpermute_b32 v84, v69, v76
	ds_bpermute_b32 v85, v69, v77
	s_waitcnt lgkmcnt(7)
	v_add_f32_e32 v70, v70, v78
	s_waitcnt lgkmcnt(6)
	v_add_f32_e32 v71, v71, v79
	s_waitcnt lgkmcnt(5)
	v_add_f32_e32 v72, v72, v80
	s_waitcnt lgkmcnt(4)
	v_add_f32_e32 v73, v73, v81
	s_waitcnt lgkmcnt(3)
	v_add_f32_e32 v74, v74, v82
	s_waitcnt lgkmcnt(2)
	v_add_f32_e32 v75, v75, v83
	s_waitcnt lgkmcnt(1)
	v_add_f32_e32 v76, v76, v84
	s_waitcnt lgkmcnt(0)
; __device__ __forceinline__ unsigned cvt_pk_bf16(float lo, float hi) { unsigned r; asm("v_cvt_pk_bf16_f32 %0, %1, %2" : "=v"(r) : "v"(lo), "v"(hi)); return r; }
; __device__ __forceinline__ void prep_phase(bf16_t* P, const float* qg, const float* kvg, const float* cs, int gw, int NGW, int lane) {
;     ...
;             const float rs = __builtin_amdgcn_rsqf(wave_sum(ss) * (1.0f / 512.0f) + EPS);
;             const f32x4 g0 = *(const f32x4*)g, g1 = *(const f32x4*)(g + 4);
;             u32x4 o; o.x = cvt_pk_bf16(v[0] * rs * g0[0], v[1] * rs * g0[1]); o.y = cvt_pk_bf16(v[2] * rs * g0[2], v[3] * rs * g0[3]);
;             o.z = cvt_pk_bf16(v[4] * rs * g1[0], v[5] * rs * g1[1]); o.w = cvt_pk_bf16(v[6] * rs * g1[2], v[7] * rs * g1[3]);
;             *(u32x4*)q = o;
	v_add_f32_e32 v77, v77, v85
	v_fmamk_f32 v70, v70, 0x3b000000, v189
	v_fmamk_f32 v71, v71, 0x3b000000, v189
	v_fmamk_f32 v72, v72, 0x3b000000, v189
	v_fmamk_f32 v73, v73, 0x3b000000, v189
	v_fmamk_f32 v74, v74, 0x3b000000, v189
	v_fmamk_f32 v75, v75, 0x3b000000, v189
	v_fmamk_f32 v76, v76, 0x3b000000, v189
	v_fmamk_f32 v77, v77, 0x3b000000, v189
	v_rsq_f32_e32 v70, v70
	v_rsq_f32_e32 v71, v71
	v_rsq_f32_e32 v72, v72
	v_rsq_f32_e32 v73, v73
	v_rsq_f32_e32 v74, v74
	v_rsq_f32_e32 v75, v75
	v_rsq_f32_e32 v76, v76
	v_rsq_f32_e32 v77, v77
	s_nop 0
	v_mul_f32_e32 v102, v70, v102
	v_mul_f32_e32 v103, v70, v103
	v_mul_f32_e32 v104, v70, v104
	v_mul_f32_e32 v105, v70, v105
	v_mul_f32_e32 v106, v70, v106
	v_mul_f32_e32 v107, v70, v107
	v_mul_f32_e32 v108, v70, v108
	v_mul_f32_e32 v109, v70, v109
	v_mul_f32_e32 v102, v86, v102
	v_mul_f32_e32 v103, v87, v103
	v_mul_f32_e32 v104, v88, v104
	v_mul_f32_e32 v105, v89, v105
	v_mul_f32_e32 v106, v90, v106
	v_mul_f32_e32 v107, v91, v107
	v_mul_f32_e32 v108, v92, v108
	v_mul_f32_e32 v109, v93, v109
	v_cvt_pk_bf16_f32 v16, v102, v103
	v_cvt_pk_bf16_f32 v17, v104, v105
	v_cvt_pk_bf16_f32 v18, v106, v107
	v_cvt_pk_bf16_f32 v19, v108, v109
	global_store_dwordx4 v1, v[16:19], s[30:31]
	v_mul_f32_e32 v110, v71, v110
	v_mul_f32_e32 v111, v71, v111
	v_mul_f32_e32 v112, v71, v112
	v_mul_f32_e32 v113, v71, v113
	v_mul_f32_e32 v114, v71, v114
	v_mul_f32_e32 v115, v71, v115
	v_mul_f32_e32 v116, v71, v116
	v_mul_f32_e32 v117, v71, v117
	v_mul_f32_e32 v110, v94, v110
	v_mul_f32_e32 v111, v95, v111
	v_mul_f32_e32 v112, v96, v112
	v_mul_f32_e32 v113, v97, v113
	v_mul_f32_e32 v114, v98, v114
	v_mul_f32_e32 v115, v99, v115
	v_mul_f32_e32 v116, v100, v116
	v_mul_f32_e32 v117, v101, v117
	v_cvt_pk_bf16_f32 v20, v110, v111
	v_cvt_pk_bf16_f32 v21, v112, v113
	v_cvt_pk_bf16_f32 v22, v114, v115
	v_cvt_pk_bf16_f32 v23, v116, v117
	global_store_dwordx4 v1, v[20:23], s[30:31] offset:1024
	v_mul_f32_e32 v118, v72, v118
	v_mul_f32_e32 v119, v72, v119
	v_mul_f32_e32 v120, v72, v120
	v_mul_f32_e32 v121, v72, v121
	v_mul_f32_e32 v122, v72, v122
	v_mul_f32_e32 v123, v72, v123
	v_mul_f32_e32 v124, v72, v124
	v_mul_f32_e32 v125, v72, v125
	v_mul_f32_e32 v118, v86, v118
	v_mul_f32_e32 v119, v87, v119
	v_mul_f32_e32 v120, v88, v120
	v_mul_f32_e32 v121, v89, v121
	v_mul_f32_e32 v122, v90, v122
	v_mul_f32_e32 v123, v91, v123
	v_mul_f32_e32 v124, v92, v124
	v_mul_f32_e32 v125, v93, v125
	v_cvt_pk_bf16_f32 v24, v118, v119
	v_cvt_pk_bf16_f32 v25, v120, v121
	v_cvt_pk_bf16_f32 v26, v122, v123
	v_cvt_pk_bf16_f32 v27, v124, v125
	global_store_dwordx4 v2, v[24:27], s[30:31]
	v_mul_f32_e32 v126, v73, v126
	v_mul_f32_e32 v127, v73, v127
	v_mul_f32_e32 v128, v73, v128
	v_mul_f32_e32 v129, v73, v129
	v_mul_f32_e32 v130, v73, v130
	v_mul_f32_e32 v131, v73, v131
	v_mul_f32_e32 v132, v73, v132
	v_mul_f32_e32 v133, v73, v133
	v_mul_f32_e32 v126, v94, v126
	v_mul_f32_e32 v127, v95, v127
	v_mul_f32_e32 v128, v96, v128
	v_mul_f32_e32 v129, v97, v129
	v_mul_f32_e32 v130, v98, v130
	v_mul_f32_e32 v131, v99, v131
	v_mul_f32_e32 v132, v100, v132
	v_mul_f32_e32 v133, v101, v133
	v_cvt_pk_bf16_f32 v28, v126, v127
	v_cvt_pk_bf16_f32 v29, v128, v129
	v_cvt_pk_bf16_f32 v30, v130, v131
	v_cvt_pk_bf16_f32 v31, v132, v133
	global_store_dwordx4 v2, v[28:31], s[30:31] offset:1024
	v_mul_f32_e32 v134, v74, v134
	v_mul_f32_e32 v135, v74, v135
	v_mul_f32_e32 v136, v74, v136
	v_mul_f32_e32 v137, v74, v137
	v_mul_f32_e32 v138, v74, v138
	v_mul_f32_e32 v139, v74, v139
	v_mul_f32_e32 v140, v74, v140
	v_mul_f32_e32 v141, v74, v141
	v_mul_f32_e32 v134, v86, v134
	v_mul_f32_e32 v135, v87, v135
	v_mul_f32_e32 v136, v88, v136
	v_mul_f32_e32 v137, v89, v137
	v_mul_f32_e32 v138, v90, v138
	v_mul_f32_e32 v139, v91, v139
	v_mul_f32_e32 v140, v92, v140
; __device__ __forceinline__ unsigned cvt_pk_bf16(float lo, float hi) { unsigned r; asm("v_cvt_pk_bf16_f32 %0, %1, %2" : "=v"(r) : "v"(lo), "v"(hi)); return r; }
; __device__ __forceinline__ float bf_lo(unsigned u) { return __uint_as_float(u << 16); }
; __device__ __forceinline__ void prep_phase(bf16_t* P, const float* qg, const float* kvg, const float* cs, int gw, int NGW, int lane) {
;     ...
;             u32x4 o; o.x = cvt_pk_bf16(v[0] * rs * g0[0], v[1] * rs * g0[1]); o.y = cvt_pk_bf16(v[2] * rs * g0[2], v[3] * rs * g0[3]);
;             o.z = cvt_pk_bf16(v[4] * rs * g1[0], v[5] * rs * g1[1]); o.w = cvt_pk_bf16(v[6] * rs * g1[2], v[7] * rs * g1[3]);
;             *(u32x4*)q = o;
;         }
;         if (lane < 32) {
;             const float x1 = bf_lo((unsigned)pr[OFF_KR + lane]), x2 = bf_lo((unsigned)pr[OFF_KR + 32 + lane]);
;             const f32x2 c = *(const f32x2*)(cs + (size_t)m * 64 + lane * 2);
;             *(unsigned*)(pr + OFF_KPE + 2 * lane) = cvt_pk_bf16(x1 * c[0] - x2 * c[1], x2 * c[0] + x1 * c[1]);
;         }
;     }
	v_mul_f32_e32 v141, v93, v141
	v_cvt_pk_bf16_f32 v32, v134, v135
	v_cvt_pk_bf16_f32 v33, v136, v137
	v_cvt_pk_bf16_f32 v34, v138, v139
	v_cvt_pk_bf16_f32 v35, v140, v141
	global_store_dwordx4 v3, v[32:35], s[30:31]
	v_mul_f32_e32 v142, v75, v142
	v_mul_f32_e32 v143, v75, v143
	v_mul_f32_e32 v144, v75, v144
	v_mul_f32_e32 v145, v75, v145
	v_mul_f32_e32 v146, v75, v146
	v_mul_f32_e32 v147, v75, v147
	v_mul_f32_e32 v148, v75, v148
	v_mul_f32_e32 v149, v75, v149
	v_mul_f32_e32 v142, v94, v142
	v_mul_f32_e32 v143, v95, v143
	v_mul_f32_e32 v144, v96, v144
	v_mul_f32_e32 v145, v97, v145
	v_mul_f32_e32 v146, v98, v146
	v_mul_f32_e32 v147, v99, v147
	v_mul_f32_e32 v148, v100, v148
	v_mul_f32_e32 v149, v101, v149
	v_cvt_pk_bf16_f32 v36, v142, v143
	v_cvt_pk_bf16_f32 v37, v144, v145
	v_cvt_pk_bf16_f32 v38, v146, v147
	v_cvt_pk_bf16_f32 v39, v148, v149
	global_store_dwordx4 v3, v[36:39], s[30:31] offset:1024
	v_mul_f32_e32 v150, v76, v150
	v_mul_f32_e32 v151, v76, v151
	v_mul_f32_e32 v152, v76, v152
	v_mul_f32_e32 v153, v76, v153
	v_mul_f32_e32 v154, v76, v154
	v_mul_f32_e32 v155, v76, v155
	v_mul_f32_e32 v156, v76, v156
	v_mul_f32_e32 v157, v76, v157
	v_mul_f32_e32 v150, v86, v150
	v_mul_f32_e32 v151, v87, v151
	v_mul_f32_e32 v152, v88, v152
	v_mul_f32_e32 v153, v89, v153
	v_mul_f32_e32 v154, v90, v154
	v_mul_f32_e32 v155, v91, v155
	v_mul_f32_e32 v156, v92, v156
	v_mul_f32_e32 v157, v93, v157
	v_cvt_pk_bf16_f32 v40, v150, v151
	v_cvt_pk_bf16_f32 v41, v152, v153
	v_cvt_pk_bf16_f32 v42, v154, v155
	v_cvt_pk_bf16_f32 v43, v156, v157
	global_store_dwordx4 v4, v[40:43], s[30:31]
	v_mul_f32_e32 v158, v77, v158
	v_mul_f32_e32 v159, v77, v159
	v_mul_f32_e32 v160, v77, v160
	v_mul_f32_e32 v161, v77, v161
	v_mul_f32_e32 v162, v77, v162
	v_mul_f32_e32 v163, v77, v163
	v_mul_f32_e32 v164, v77, v164
	v_mul_f32_e32 v165, v77, v165
	v_mul_f32_e32 v158, v94, v158
	v_mul_f32_e32 v159, v95, v159
	v_mul_f32_e32 v160, v96, v160
	v_mul_f32_e32 v161, v97, v161
	v_mul_f32_e32 v162, v98, v162
	v_mul_f32_e32 v163, v99, v163
	v_mul_f32_e32 v164, v100, v164
	v_mul_f32_e32 v165, v101, v165
	v_cvt_pk_bf16_f32 v44, v158, v159
	v_cvt_pk_bf16_f32 v45, v160, v161
	v_cvt_pk_bf16_f32 v46, v162, v163
	v_cvt_pk_bf16_f32 v47, v164, v165
	global_store_dwordx4 v4, v[44:47], s[30:31] offset:1024
	v_lshlrev_b32_e32 v48, 16, v48
	v_lshlrev_b32_e32 v52, 16, v52
	v_mul_f32_e32 v78, v56, v48
	v_mul_f32_e32 v79, v57, v52
	v_mul_f32_e32 v80, v57, v48
	v_mul_f32_e32 v81, v56, v52
	v_sub_f32_e32 v78, v78, v79
	v_add_f32_e32 v80, v80, v81
	v_cvt_pk_bf16_f32 v48, v78, v80
	v_add_u32_e32 v5, v5, v0
	v_lshlrev_b32_e32 v49, 16, v49
	v_lshlrev_b32_e32 v53, 16, v53
	v_mul_f32_e32 v82, v58, v49
	v_mul_f32_e32 v83, v59, v53
	v_mul_f32_e32 v84, v59, v49
	v_mul_f32_e32 v85, v58, v53
	v_sub_f32_e32 v82, v82, v83
	v_add_f32_e32 v84, v84, v85
	v_cvt_pk_bf16_f32 v49, v82, v84
	v_add_u32_e32 v6, v6, v0
	v_lshlrev_b32_e32 v50, 16, v50
	v_lshlrev_b32_e32 v54, 16, v54
	v_mul_f32_e32 v78, v60, v50
	v_mul_f32_e32 v79, v61, v54
	v_mul_f32_e32 v80, v61, v50
	v_mul_f32_e32 v81, v60, v54
	v_sub_f32_e32 v78, v78, v79
	v_add_f32_e32 v80, v80, v81
	v_cvt_pk_bf16_f32 v50, v78, v80
	v_add_u32_e32 v7, v7, v0
	v_lshlrev_b32_e32 v51, 16, v51
	v_lshlrev_b32_e32 v55, 16, v55
	v_mul_f32_e32 v82, v62, v51
	v_mul_f32_e32 v83, v63, v55
	v_mul_f32_e32 v84, v63, v51
	v_mul_f32_e32 v85, v62, v55
	v_sub_f32_e32 v82, v82, v83
	v_add_f32_e32 v84, v84, v85
	v_cvt_pk_bf16_f32 v51, v82, v84
	v_add_u32_e32 v8, v8, v0
	s_mov_b32 exec_hi, 0
	global_store_dword v5, v48, s[30:31]
	global_store_dword v6, v49, s[30:31]
	global_store_dword v7, v50, s[30:31]
	global_store_dword v8, v51, s[30:31]
	s_mov_b64 exec, -1
	s_lshl_b32 s17, s16, 2
	s_add_i32 s3, s3, s17
	s_cmp_lt_i32 s3, 0x8000
	s_cbranch_scc1 .Lprep_rows
